# up epilogue: merge the two half-row dwordx2 stores per row chunk into one dwordx4 store (on top of v016)
# baseline (speedup 1.0000x reference)
.LBB0_139:
	v_lshl_add_u32 v151, s36, 2, v150
	ds_read_b128 v[158:161], v151
	ds_read_b128 v[162:165], v151 offset:1040
	ds_read_b128 v[166:169], v151 offset:2080
	s_waitcnt lgkmcnt(2)
	v_pk_mul_f32 v[160:161], v[160:161], v[210:211]
	v_pk_mul_f32 v[158:159], v[158:159], v[208:209]
	s_waitcnt lgkmcnt(1)
	v_pk_mul_f32 v[164:165], v[164:165], v[214:215]
	v_pk_mul_f32 v[162:163], v[162:163], v[212:213]
	v_pk_fma_f32 v[160:161], v[152:153], v[160:161], v[164:165]
	v_pk_fma_f32 v[158:159], v[146:147], v[158:159], v[162:163]
	s_waitcnt lgkmcnt(0)
	v_pk_mul_f32 v[162:163], v[168:169], v[218:219]
	v_pk_mul_f32 v[164:165], v[166:167], v[216:217]
	v_pk_fma_f32 v[160:161], v[154:155], v[162:163], v[160:161]
	v_pk_fma_f32 v[162:163], v[148:149], v[164:165], v[158:159]
	v_pk_add_f32 v[158:159], v[222:223], v[160:161]
	v_pk_add_f32 v[160:161], v[220:221], v[162:163]
	ds_read_b128 v[162:165], v151 offset:512
	ds_read_b128 v[166:169], v151 offset:1552
	ds_read_b128 v[170:173], v151 offset:2592
	s_waitcnt lgkmcnt(2)
	v_pk_mul_f32 v[164:165], v[164:165], v[226:227]
	v_pk_mul_f32 v[162:163], v[162:163], v[224:225]
	s_waitcnt lgkmcnt(1)
	v_pk_mul_f32 v[168:169], v[168:169], v[234:235]
	v_pk_mul_f32 v[166:167], v[166:167], v[232:233]
	v_pk_fma_f32 v[164:165], v[152:153], v[164:165], v[168:169]
	v_pk_fma_f32 v[162:163], v[146:147], v[162:163], v[166:167]
	s_waitcnt lgkmcnt(0)
	v_pk_mul_f32 v[166:167], v[172:173], v[246:247]
	v_pk_mul_f32 v[168:169], v[170:171], v[244:245]
	v_pk_fma_f32 v[164:165], v[154:155], v[166:167], v[164:165]
	v_pk_fma_f32 v[166:167], v[148:149], v[168:169], v[162:163]
	v_pk_add_f32 v[162:163], v[250:251], v[164:165]
	v_pk_add_f32 v[164:165], v[248:249], v[166:167]
	v_mov_b64_e32 v[170:171], s[74:75]
	v_fma_f32 v151, |v164|, s1, 1.0
	v_rcp_f32_e32 v166, v151
	v_mul_f32_e32 v151, v164, v164
	v_mul_f32_e32 v151, 0xbf38aa3b, v151
	v_exp_f32_e32 v168, v151
	v_fma_f32 v151, |v165|, s1, 1.0
	v_rcp_f32_e32 v167, v151
	v_mul_f32_e32 v151, v165, v165
	v_mul_f32_e32 v151, 0xbf38aa3b, v151
	v_exp_f32_e32 v169, v151
	v_pk_fma_f32 v[172:173], v[166:167], s[22:23], v[170:171] op_sel_hi:[1,0,0]
	v_cmp_gt_f32_e32 vcc, 0, v164
	v_pk_fma_f32 v[172:173], v[166:167], v[172:173], s[24:25] op_sel_hi:[1,1,0]
	v_cmp_gt_f32_e64 s[38:39], 0, v165
	v_pk_fma_f32 v[172:173], v[166:167], v[172:173], s[26:27] op_sel_hi:[1,1,0]
	v_fma_f32 v151, |v162|, s1, 1.0
	v_pk_fma_f32 v[172:173], v[166:167], v[172:173], s[0:1] op_sel_hi:[1,1,0]
	s_nop 0
	v_pk_mul_f32 v[166:167], v[166:167], v[172:173]
	s_nop 0
	v_pk_mul_f32 v[166:167], v[168:169], v[166:167]
	s_nop 0
	v_pk_mul_f32 v[168:169], v[164:165], v[166:167]
	v_pk_fma_f32 v[164:165], v[164:165], v[166:167], v[164:165] neg_lo:[1,0,0] neg_hi:[1,0,0]
	s_nop 0
	v_cndmask_b32_e64 v165, v165, v169, s[38:39]
	v_cndmask_b32_e32 v164, v164, v168, vcc
	v_pk_mul_f32 v[160:161], v[160:161], v[164:165]
	v_rcp_f32_e32 v164, v151
	v_mul_f32_e32 v151, v162, v162
	v_mul_f32_e32 v151, 0xbf38aa3b, v151
	v_exp_f32_e32 v166, v151
	v_fma_f32 v151, |v163|, s1, 1.0
	v_rcp_f32_e32 v165, v151
	v_mul_f32_e32 v151, v163, v163
	v_mul_f32_e32 v151, 0xbf38aa3b, v151
	v_exp_f32_e32 v167, v151
	v_pk_fma_f32 v[168:169], v[164:165], s[22:23], v[170:171] op_sel_hi:[1,0,0]
	v_cmp_gt_f32_e32 vcc, 0, v162
	v_pk_fma_f32 v[168:169], v[164:165], v[168:169], s[24:25] op_sel_hi:[1,1,0]
	v_cmp_gt_f32_e64 s[38:39], 0, v163
	v_pk_fma_f32 v[168:169], v[164:165], v[168:169], s[26:27] op_sel_hi:[1,1,0]
	v_cvt_pk_bf16_f32 v160, v160, v161
	v_pk_fma_f32 v[168:169], v[164:165], v[168:169], s[0:1] op_sel_hi:[1,1,0]
	s_nop 0
	v_pk_mul_f32 v[164:165], v[164:165], v[168:169]
	s_nop 0
	v_pk_mul_f32 v[164:165], v[166:167], v[164:165]
	s_nop 0
	v_pk_mul_f32 v[166:167], v[162:163], v[164:165]
	v_pk_fma_f32 v[162:163], v[162:163], v[164:165], v[162:163] neg_lo:[1,0,0] neg_hi:[1,0,0]
	s_nop 0
	v_cndmask_b32_e64 v163, v163, v167, s[38:39]
	v_cndmask_b32_e32 v162, v162, v166, vcc
	v_pk_mul_f32 v[158:159], v[158:159], v[162:163]
	v_cvt_pk_bf16_f32 v236, v158, v159
	v_mov_b32_e32 v228, v160
	s_mov_b32 s36, 4
	v_lshl_add_u32 v151, s36, 2, v150
	ds_read_b128 v[158:161], v151
	ds_read_b128 v[162:165], v151 offset:1040
	ds_read_b128 v[166:169], v151 offset:2080
	s_waitcnt lgkmcnt(2)
	v_pk_mul_f32 v[160:161], v[160:161], v[138:139]
	v_pk_mul_f32 v[158:159], v[158:159], v[136:137]
	s_waitcnt lgkmcnt(1)
	v_pk_mul_f32 v[164:165], v[164:165], v[142:143]
	v_pk_mul_f32 v[162:163], v[162:163], v[140:141]
	v_pk_fma_f32 v[160:161], v[152:153], v[160:161], v[164:165]
	v_pk_fma_f32 v[158:159], v[146:147], v[158:159], v[162:163]
	s_waitcnt lgkmcnt(0)
	v_pk_mul_f32 v[162:163], v[168:169], v[130:131]
	v_pk_mul_f32 v[164:165], v[166:167], v[128:129]
	v_pk_fma_f32 v[160:161], v[154:155], v[162:163], v[160:161]
	v_pk_fma_f32 v[162:163], v[148:149], v[164:165], v[158:159]
	v_pk_add_f32 v[158:159], v[134:135], v[160:161]
	v_pk_add_f32 v[160:161], v[132:133], v[162:163]
	ds_read_b128 v[162:165], v151 offset:512
	ds_read_b128 v[166:169], v151 offset:1552
	ds_read_b128 v[170:173], v151 offset:2592
	s_waitcnt lgkmcnt(2)
	v_pk_mul_f32 v[164:165], v[164:165], v[180:181]
	v_pk_mul_f32 v[162:163], v[162:163], v[178:179]
	s_waitcnt lgkmcnt(1)
	v_pk_mul_f32 v[168:169], v[168:169], v[184:185]
	v_pk_mul_f32 v[166:167], v[166:167], v[182:183]
	v_pk_fma_f32 v[164:165], v[152:153], v[164:165], v[168:169]
	v_pk_fma_f32 v[162:163], v[146:147], v[162:163], v[166:167]
	s_waitcnt lgkmcnt(0)
	v_pk_mul_f32 v[166:167], v[172:173], v[200:201]
	v_pk_mul_f32 v[168:169], v[170:171], v[198:199]
	v_pk_fma_f32 v[164:165], v[154:155], v[166:167], v[164:165]
	v_pk_fma_f32 v[166:167], v[148:149], v[168:169], v[162:163]
	v_pk_add_f32 v[162:163], v[206:207], v[164:165]
	v_pk_add_f32 v[164:165], v[204:205], v[166:167]
	v_mov_b64_e32 v[170:171], s[74:75]
	v_fma_f32 v151, |v164|, s1, 1.0
	v_rcp_f32_e32 v166, v151
	v_mul_f32_e32 v151, v164, v164
	v_mul_f32_e32 v151, 0xbf38aa3b, v151
	v_exp_f32_e32 v168, v151
	v_fma_f32 v151, |v165|, s1, 1.0
	v_rcp_f32_e32 v167, v151
	v_mul_f32_e32 v151, v165, v165
	v_mul_f32_e32 v151, 0xbf38aa3b, v151
	v_exp_f32_e32 v169, v151
	v_pk_fma_f32 v[172:173], v[166:167], s[22:23], v[170:171] op_sel_hi:[1,0,0]
	v_cmp_gt_f32_e32 vcc, 0, v164
	v_pk_fma_f32 v[172:173], v[166:167], v[172:173], s[24:25] op_sel_hi:[1,1,0]
	v_cmp_gt_f32_e64 s[38:39], 0, v165
	v_pk_fma_f32 v[172:173], v[166:167], v[172:173], s[26:27] op_sel_hi:[1,1,0]
	v_fma_f32 v151, |v162|, s1, 1.0
	v_pk_fma_f32 v[172:173], v[166:167], v[172:173], s[0:1] op_sel_hi:[1,1,0]
	s_nop 0
	v_pk_mul_f32 v[166:167], v[166:167], v[172:173]
	s_nop 0
	v_pk_mul_f32 v[166:167], v[168:169], v[166:167]
	s_nop 0
	v_pk_mul_f32 v[168:169], v[164:165], v[166:167]
	v_pk_fma_f32 v[164:165], v[164:165], v[166:167], v[164:165] neg_lo:[1,0,0] neg_hi:[1,0,0]
	s_nop 0
	v_cndmask_b32_e64 v165, v165, v169, s[38:39]
	v_cndmask_b32_e32 v164, v164, v168, vcc
	v_pk_mul_f32 v[160:161], v[160:161], v[164:165]
	v_rcp_f32_e32 v164, v151
	v_mul_f32_e32 v151, v162, v162
	v_mul_f32_e32 v151, 0xbf38aa3b, v151
	v_exp_f32_e32 v166, v151
	v_fma_f32 v151, |v163|, s1, 1.0
	v_rcp_f32_e32 v165, v151
	v_mul_f32_e32 v151, v163, v163
	v_mul_f32_e32 v151, 0xbf38aa3b, v151
	v_exp_f32_e32 v167, v151
	v_pk_fma_f32 v[168:169], v[164:165], s[22:23], v[170:171] op_sel_hi:[1,0,0]
	v_cmp_gt_f32_e32 vcc, 0, v162
	v_pk_fma_f32 v[168:169], v[164:165], v[168:169], s[24:25] op_sel_hi:[1,1,0]
	v_cmp_gt_f32_e64 s[38:39], 0, v163
	v_pk_fma_f32 v[168:169], v[164:165], v[168:169], s[26:27] op_sel_hi:[1,1,0]
	v_cvt_pk_bf16_f32 v160, v160, v161
	v_pk_fma_f32 v[168:169], v[164:165], v[168:169], s[0:1] op_sel_hi:[1,1,0]
	s_nop 0
	v_pk_mul_f32 v[164:165], v[164:165], v[168:169]
	s_nop 0
	v_pk_mul_f32 v[164:165], v[166:167], v[164:165]
	s_nop 0
	v_pk_mul_f32 v[166:167], v[162:163], v[164:165]
	v_pk_fma_f32 v[162:163], v[162:163], v[164:165], v[162:163] neg_lo:[1,0,0] neg_hi:[1,0,0]
	s_nop 0
	v_cndmask_b32_e64 v163, v163, v167, s[38:39]
	v_cndmask_b32_e32 v162, v162, v166, vcc
	v_pk_mul_f32 v[158:159], v[158:159], v[162:163]
	v_cvt_pk_bf16_f32 v161, v158, v159
	v_mov_b32_e32 v158, v228
	v_mov_b32_e32 v159, v236
	global_store_dwordx4 v[156:157], v[158:161], off
	s_nop 1
	s_branch .LBB0_136

.LBB0_148:
	s_lshl_b32 s13, s36, 2
	v_add_u32_e32 v40, s13, v18
	v_add_u32_e32 v41, s13, v19
	ds_read_b128 v[10:13], v40
	ds_read_b128 v[14:17], v41
	ds_read_b128 v[20:23], v40 offset:2080
	s_waitcnt lgkmcnt(2)
	v_pk_mul_f32 v[12:13], v[12:13], v[210:211]
	v_pk_mul_f32 v[10:11], v[10:11], v[208:209]
	s_waitcnt lgkmcnt(1)
	v_pk_mul_f32 v[16:17], v[16:17], v[214:215]
	v_pk_mul_f32 v[14:15], v[14:15], v[212:213]
	v_pk_fma_f32 v[12:13], v[4:5], v[12:13], v[16:17]
	v_pk_fma_f32 v[10:11], v[0:1], v[10:11], v[14:15]
	s_waitcnt lgkmcnt(0)
	v_pk_mul_f32 v[14:15], v[22:23], v[218:219]
	v_pk_mul_f32 v[16:17], v[20:21], v[216:217]
	v_pk_fma_f32 v[12:13], v[6:7], v[14:15], v[12:13]
	v_pk_fma_f32 v[14:15], v[2:3], v[16:17], v[10:11]
	v_pk_add_f32 v[10:11], v[222:223], v[12:13]
	v_pk_add_f32 v[12:13], v[220:221], v[14:15]
	ds_read_b128 v[14:17], v40 offset:512
	ds_read_b128 v[20:23], v41 offset:512
	ds_read_b128 v[24:27], v40 offset:2592
	s_waitcnt lgkmcnt(2)
	v_pk_mul_f32 v[16:17], v[16:17], v[226:227]
	v_pk_mul_f32 v[14:15], v[14:15], v[224:225]
	s_waitcnt lgkmcnt(1)
	v_pk_mul_f32 v[22:23], v[22:23], v[234:235]
	v_pk_mul_f32 v[20:21], v[20:21], v[232:233]
	v_pk_fma_f32 v[16:17], v[4:5], v[16:17], v[22:23]
	v_pk_fma_f32 v[14:15], v[0:1], v[14:15], v[20:21]
	s_waitcnt lgkmcnt(0)
	v_pk_mul_f32 v[20:21], v[26:27], v[246:247]
	v_pk_mul_f32 v[22:23], v[24:25], v[244:245]
	v_pk_fma_f32 v[16:17], v[6:7], v[20:21], v[16:17]
	v_pk_fma_f32 v[20:21], v[2:3], v[22:23], v[14:15]
	v_mov_b64_e32 v[24:25], s[74:75]
	v_pk_add_f32 v[14:15], v[250:251], v[16:17]
	v_pk_add_f32 v[16:17], v[248:249], v[20:21]
	s_nop 0
	v_mul_f32_e32 v21, v16, v16
	v_mul_f32_e32 v21, 0xbf38aa3b, v21
	v_fma_f32 v20, |v16|, s1, 1.0
	v_exp_f32_e32 v22, v21
	v_fma_f32 v21, |v17|, s1, 1.0
	v_rcp_f32_e32 v20, v20
	v_rcp_f32_e32 v21, v21
	v_mul_f32_e32 v23, v17, v17
	v_mul_f32_e32 v23, 0xbf38aa3b, v23
	v_exp_f32_e32 v23, v23
	v_pk_fma_f32 v[26:27], v[20:21], s[22:23], v[24:25] op_sel_hi:[1,0,0]
	v_cmp_gt_f32_e32 vcc, 0, v16
	v_pk_fma_f32 v[26:27], v[20:21], v[26:27], s[24:25] op_sel_hi:[1,1,0]
	v_cmp_gt_f32_e64 s[38:39], 0, v17
	v_pk_fma_f32 v[26:27], v[20:21], v[26:27], s[26:27] op_sel_hi:[1,1,0]
	s_nop 0
	v_pk_fma_f32 v[26:27], v[20:21], v[26:27], s[0:1] op_sel_hi:[1,1,0]
	s_nop 0
	v_pk_mul_f32 v[20:21], v[20:21], v[26:27]
	s_nop 0
	v_pk_mul_f32 v[20:21], v[22:23], v[20:21]
	s_nop 0
	v_pk_mul_f32 v[22:23], v[16:17], v[20:21]
	v_pk_fma_f32 v[16:17], v[16:17], v[20:21], v[16:17] neg_lo:[1,0,0] neg_hi:[1,0,0]
	s_nop 0
	v_cndmask_b32_e64 v17, v17, v23, s[38:39]
	v_cndmask_b32_e32 v16, v16, v22, vcc
	v_pk_mul_f32 v[12:13], v[12:13], v[16:17]
	v_cmp_gt_f32_e32 vcc, 0, v14
	v_cvt_pk_bf16_f32 v12, v12, v13
	v_fma_f32 v13, |v14|, s1, 1.0
	v_rcp_f32_e32 v16, v13
	v_mul_f32_e32 v13, v14, v14
	v_mul_f32_e32 v13, 0xbf38aa3b, v13
	v_exp_f32_e32 v20, v13
	v_fma_f32 v13, |v15|, s1, 1.0
	v_rcp_f32_e32 v17, v13
	v_mul_f32_e32 v13, v15, v15
	v_mul_f32_e32 v13, 0xbf38aa3b, v13
	v_exp_f32_e32 v21, v13
	v_pk_fma_f32 v[22:23], v[16:17], s[22:23], v[24:25] op_sel_hi:[1,0,0]
	v_cmp_gt_f32_e64 s[38:39], 0, v15
	v_pk_fma_f32 v[22:23], v[16:17], v[22:23], s[24:25] op_sel_hi:[1,1,0]
	s_nop 0
	v_pk_fma_f32 v[22:23], v[16:17], v[22:23], s[26:27] op_sel_hi:[1,1,0]
	s_nop 0
	v_pk_fma_f32 v[22:23], v[16:17], v[22:23], s[0:1] op_sel_hi:[1,1,0]
	s_nop 0
	v_pk_mul_f32 v[16:17], v[16:17], v[22:23]
	s_nop 0
	v_pk_mul_f32 v[16:17], v[20:21], v[16:17]
	s_nop 0
	v_pk_mul_f32 v[20:21], v[14:15], v[16:17]
	v_pk_fma_f32 v[14:15], v[14:15], v[16:17], v[14:15] neg_lo:[1,0,0] neg_hi:[1,0,0]
	s_nop 0
	v_cndmask_b32_e64 v15, v15, v21, s[38:39]
	v_cndmask_b32_e32 v14, v14, v20, vcc
	v_pk_mul_f32 v[10:11], v[10:11], v[14:15]
	v_cvt_pk_bf16_f32 v236, v10, v11
	v_mov_b32_e32 v228, v12
	s_mov_b32 s36, 4
	s_lshl_b32 s13, s36, 2
	v_add_u32_e32 v40, s13, v18
	v_add_u32_e32 v41, s13, v19
	ds_read_b128 v[10:13], v40
	ds_read_b128 v[14:17], v41
	ds_read_b128 v[20:23], v40 offset:2080
	s_waitcnt lgkmcnt(2)
	v_pk_mul_f32 v[12:13], v[12:13], v[138:139]
	v_pk_mul_f32 v[10:11], v[10:11], v[136:137]
	s_waitcnt lgkmcnt(1)
	v_pk_mul_f32 v[16:17], v[16:17], v[142:143]
	v_pk_mul_f32 v[14:15], v[14:15], v[140:141]
	v_pk_fma_f32 v[12:13], v[4:5], v[12:13], v[16:17]
	v_pk_fma_f32 v[10:11], v[0:1], v[10:11], v[14:15]
	s_waitcnt lgkmcnt(0)
	v_pk_mul_f32 v[14:15], v[22:23], v[130:131]
	v_pk_mul_f32 v[16:17], v[20:21], v[128:129]
	v_pk_fma_f32 v[12:13], v[6:7], v[14:15], v[12:13]
	v_pk_fma_f32 v[14:15], v[2:3], v[16:17], v[10:11]
	v_pk_add_f32 v[10:11], v[134:135], v[12:13]
	v_pk_add_f32 v[12:13], v[132:133], v[14:15]
	ds_read_b128 v[14:17], v40 offset:512
	ds_read_b128 v[20:23], v41 offset:512
	ds_read_b128 v[24:27], v40 offset:2592
	s_waitcnt lgkmcnt(2)
	v_pk_mul_f32 v[16:17], v[16:17], v[180:181]
	v_pk_mul_f32 v[14:15], v[14:15], v[178:179]
	s_waitcnt lgkmcnt(1)
	v_pk_mul_f32 v[22:23], v[22:23], v[184:185]
	v_pk_mul_f32 v[20:21], v[20:21], v[182:183]
	v_pk_fma_f32 v[16:17], v[4:5], v[16:17], v[22:23]
	v_pk_fma_f32 v[14:15], v[0:1], v[14:15], v[20:21]
	s_waitcnt lgkmcnt(0)
	v_pk_mul_f32 v[20:21], v[26:27], v[200:201]
	v_pk_mul_f32 v[22:23], v[24:25], v[198:199]
	v_pk_fma_f32 v[16:17], v[6:7], v[20:21], v[16:17]
	v_pk_fma_f32 v[20:21], v[2:3], v[22:23], v[14:15]
	v_mov_b64_e32 v[24:25], s[74:75]
	v_pk_add_f32 v[14:15], v[206:207], v[16:17]
	v_pk_add_f32 v[16:17], v[204:205], v[20:21]
	s_nop 0
	v_mul_f32_e32 v21, v16, v16
	v_mul_f32_e32 v21, 0xbf38aa3b, v21
	v_fma_f32 v20, |v16|, s1, 1.0
	v_exp_f32_e32 v22, v21
	v_fma_f32 v21, |v17|, s1, 1.0
	v_rcp_f32_e32 v20, v20
	v_rcp_f32_e32 v21, v21
	v_mul_f32_e32 v23, v17, v17
	v_mul_f32_e32 v23, 0xbf38aa3b, v23
	v_exp_f32_e32 v23, v23
	v_pk_fma_f32 v[26:27], v[20:21], s[22:23], v[24:25] op_sel_hi:[1,0,0]
	v_cmp_gt_f32_e32 vcc, 0, v16
	v_pk_fma_f32 v[26:27], v[20:21], v[26:27], s[24:25] op_sel_hi:[1,1,0]
	v_cmp_gt_f32_e64 s[38:39], 0, v17
	v_pk_fma_f32 v[26:27], v[20:21], v[26:27], s[26:27] op_sel_hi:[1,1,0]
	s_nop 0
	v_pk_fma_f32 v[26:27], v[20:21], v[26:27], s[0:1] op_sel_hi:[1,1,0]
	s_nop 0
	v_pk_mul_f32 v[20:21], v[20:21], v[26:27]
	s_nop 0
	v_pk_mul_f32 v[20:21], v[22:23], v[20:21]
	s_nop 0
	v_pk_mul_f32 v[22:23], v[16:17], v[20:21]
	v_pk_fma_f32 v[16:17], v[16:17], v[20:21], v[16:17] neg_lo:[1,0,0] neg_hi:[1,0,0]
	s_nop 0
	v_cndmask_b32_e64 v17, v17, v23, s[38:39]
	v_cndmask_b32_e32 v16, v16, v22, vcc
	v_pk_mul_f32 v[12:13], v[12:13], v[16:17]
	v_cmp_gt_f32_e32 vcc, 0, v14
	v_cvt_pk_bf16_f32 v12, v12, v13
	v_fma_f32 v13, |v14|, s1, 1.0
	v_rcp_f32_e32 v16, v13
	v_mul_f32_e32 v13, v14, v14
	v_mul_f32_e32 v13, 0xbf38aa3b, v13
	v_exp_f32_e32 v20, v13
	v_fma_f32 v13, |v15|, s1, 1.0
	v_rcp_f32_e32 v17, v13
	v_mul_f32_e32 v13, v15, v15
	v_mul_f32_e32 v13, 0xbf38aa3b, v13
	v_exp_f32_e32 v21, v13
	v_pk_fma_f32 v[22:23], v[16:17], s[22:23], v[24:25] op_sel_hi:[1,0,0]
	v_cmp_gt_f32_e64 s[38:39], 0, v15
	v_pk_fma_f32 v[22:23], v[16:17], v[22:23], s[24:25] op_sel_hi:[1,1,0]
	s_nop 0
	v_pk_fma_f32 v[22:23], v[16:17], v[22:23], s[26:27] op_sel_hi:[1,1,0]
	s_nop 0
	v_pk_fma_f32 v[22:23], v[16:17], v[22:23], s[0:1] op_sel_hi:[1,1,0]
	s_nop 0
	v_pk_mul_f32 v[16:17], v[16:17], v[22:23]
	s_nop 0
	v_pk_mul_f32 v[16:17], v[20:21], v[16:17]
	s_nop 0
	v_pk_mul_f32 v[20:21], v[14:15], v[16:17]
	v_pk_fma_f32 v[14:15], v[14:15], v[16:17], v[14:15] neg_lo:[1,0,0] neg_hi:[1,0,0]
	s_nop 0
	v_cndmask_b32_e64 v15, v15, v21, s[38:39]
	v_cndmask_b32_e32 v14, v14, v20, vcc
	v_pk_mul_f32 v[10:11], v[10:11], v[14:15]
	v_cvt_pk_bf16_f32 v13, v10, v11
	v_mov_b32_e32 v10, v228
	v_mov_b32_e32 v11, v236
	global_store_dwordx4 v[8:9], v[10:13], off
	s_nop 1
	s_branch .LBB0_145
